# differential combine (old phase P3: rmsnorm(O0 - lam*O1)*subln) fused into the attention phase: a workgroup now owns both maps of its query blocks and combines its own rows after the c=1 unit; P3 and
# speedup vs baseline: 1.0019x; 1.0019x over previous
; #define LANE_WAVE() int tid_ = threadIdx.x; asm volatile("" : "+v"(tid_)); const int lane = tid_ & 63, wave = __builtin_amdgcn_readfirstlane(tid_ >> 6), gw = vcu * NWAVES + wave;
; __global__ void __launch_bounds__(NWAVES * 64, 2) mk_fwd(Args args) {
;     ...
;             { LANE_WAVE(); (void)gw; (void)wave;
;               float a0 = fabsf(ap->in[7][l * 128 + lane]), a1 = fabsf(ap->in[7][l * 128 + 64 + lane]), d0 = fabsf(ap->in[8][l * 128 + lane]), d1 = fabsf(ap->in[8][l * 128 + 64 + lane]);
; #pragma unroll
;               for (int o = 1; o < 64; o <<= 1) { a0 = fmaxf(a0, __shfl_xor(a0, o)); a1 = fmaxf(a1, __shfl_xor(a1, o)); d0 = fmaxf(d0, __shfl_xor(d0, o)); d1 = fmaxf(d1, __shfl_xor(d1, o)); }
;               nomax_swa = (8.0f * LOG2E * 1.02f * a0 * a1) <= 40.0f; nomax_diff = (8.0f * LOG2E * 1.02f * d0 * d1) <= 40.0f; }
.LBB0_244:
	s_or_b64 exec, exec, s[38:39]
	v_readlane_b32 s46, v253, 2
	v_readlane_b32 s47, v253, 3
	v_mov_b32_e32 v0, v212
	s_waitcnt lgkmcnt(0)
	s_barrier
	s_load_dwordx4 s[40:43], s[46:47], 0x38
	v_readlane_b32 s2, v252, 11
	v_xor_b32_e32 v22, 1, v215
	v_xor_b32_e32 v23, 2, v215
	v_and_or_b32 v0, v0, 63, s2
	v_lshlrev_b64 v[18:19], 2, v[0:1]
	s_waitcnt lgkmcnt(0)
	v_lshl_add_u64 v[20:21], s[40:41], 0, v[18:19]
	v_lshl_add_u64 v[18:19], s[42:43], 0, v[18:19]
	global_load_dword v0, v[20:21], off
	s_nop 0
	global_load_dword v20, v[20:21], off offset:256
	s_nop 0
	global_load_dword v21, v[18:19], off
	s_nop 0
	global_load_dword v18, v[18:19], off offset:256
	v_and_b32_e32 v19, 64, v215
	v_add_u32_e32 v19, 64, v19
	v_cmp_lt_i32_e32 vcc, v22, v19
	v_xor_b32_e32 v24, 4, v215
	v_xor_b32_e32 v25, 8, v215
	v_cndmask_b32_e32 v22, v215, v22, vcc
	v_cmp_lt_i32_e32 vcc, v23, v19
	v_xor_b32_e32 v26, 16, v215
	v_xor_b32_e32 v27, 32, v215
	v_cndmask_b32_e32 v23, v215, v23, vcc
	v_cmp_lt_i32_e32 vcc, v24, v19
	v_lshlrev_b32_e32 v187, 2, v22
	v_lshlrev_b32_e32 v200, 2, v23
	v_cndmask_b32_e32 v24, v215, v24, vcc
	v_cmp_lt_i32_e32 vcc, v25, v19
	v_lshlrev_b32_e32 v201, 2, v24
	v_readlane_b32 s3, v252, 12
	v_cndmask_b32_e32 v25, v215, v25, vcc
	v_cmp_lt_i32_e32 vcc, v26, v19
	v_lshlrev_b32_e32 v202, 2, v25
	v_readlane_b32 s2, v254, 21
	v_cndmask_b32_e32 v26, v215, v26, vcc
	v_cmp_lt_i32_e32 vcc, v27, v19
	v_lshlrev_b32_e32 v220, 2, v26
	v_readlane_b32 s3, v254, 22
	v_cndmask_b32_e32 v19, v215, v27, vcc
	v_lshlrev_b32_e32 v221, 2, v19
	s_andn2_b64 vcc, exec, s[2:3]
	s_waitcnt vmcnt(3)
	v_and_b32_e32 v22, 0x7fffffff, v0
	s_waitcnt vmcnt(2)
	v_and_b32_e32 v23, 0x7fffffff, v20
	s_waitcnt vmcnt(1)
	v_and_b32_e32 v27, 0x7fffffff, v21
	s_waitcnt vmcnt(0)
	v_and_b32_e32 v28, 0x7fffffff, v18
	ds_bpermute_b32 v22, v187, v22
	ds_bpermute_b32 v23, v187, v23
	ds_bpermute_b32 v27, v187, v27
	ds_bpermute_b32 v28, v187, v28
	v_max_f32_e64 v0, |v0|, |v0|
	v_max_f32_e64 v20, |v20|, |v20|
	v_max_f32_e64 v21, |v21|, |v21|
	v_max_f32_e64 v18, |v18|, |v18|
	s_waitcnt lgkmcnt(3)
	v_max_f32_e32 v22, v22, v22
	s_waitcnt lgkmcnt(2)
	v_max_f32_e32 v23, v23, v23
	s_waitcnt lgkmcnt(1)
	v_max_f32_e32 v27, v27, v27
	s_waitcnt lgkmcnt(0)
	v_max_f32_e32 v28, v28, v28
	v_max_f32_e32 v0, v0, v22
	v_max_f32_e32 v20, v20, v23
	v_max_f32_e32 v21, v21, v27
	v_max_f32_e32 v18, v18, v28
	ds_bpermute_b32 v22, v200, v0
	ds_bpermute_b32 v23, v200, v20
	ds_bpermute_b32 v27, v200, v21
	ds_bpermute_b32 v28, v200, v18
	s_waitcnt lgkmcnt(3)
	v_max_f32_e32 v22, v22, v22
	s_waitcnt lgkmcnt(2)
	v_max_f32_e32 v23, v23, v23
	s_waitcnt lgkmcnt(1)
	v_max_f32_e32 v24, v27, v27
	s_waitcnt lgkmcnt(0)
	v_max_f32_e32 v27, v28, v28
	v_max_f32_e32 v0, v0, v22
	v_max_f32_e32 v20, v20, v23
	v_max_f32_e32 v21, v21, v24
	v_max_f32_e32 v18, v18, v27
	ds_bpermute_b32 v22, v201, v0
	ds_bpermute_b32 v23, v201, v20
	ds_bpermute_b32 v24, v201, v21
	ds_bpermute_b32 v27, v201, v18
	s_waitcnt lgkmcnt(3)
	v_max_f32_e32 v22, v22, v22
	s_waitcnt lgkmcnt(2)
	v_max_f32_e32 v23, v23, v23
	s_waitcnt lgkmcnt(1)
	v_max_f32_e32 v24, v24, v24
	s_waitcnt lgkmcnt(0)
	v_max_f32_e32 v25, v27, v27
	v_max_f32_e32 v0, v0, v22
	v_max_f32_e32 v20, v20, v23
	v_max_f32_e32 v21, v21, v24
	v_max_f32_e32 v18, v18, v25
	ds_bpermute_b32 v22, v202, v0
	ds_bpermute_b32 v23, v202, v20
	ds_bpermute_b32 v24, v202, v21
	ds_bpermute_b32 v25, v202, v18
	s_waitcnt lgkmcnt(3)
	v_max_f32_e32 v22, v22, v22
	s_waitcnt lgkmcnt(2)
	v_max_f32_e32 v23, v23, v23
	s_waitcnt lgkmcnt(1)
	v_max_f32_e32 v24, v24, v24
	s_waitcnt lgkmcnt(0)
	v_max_f32_e32 v25, v25, v25
	v_max_f32_e32 v0, v0, v22
	v_max_f32_e32 v20, v20, v23
	v_max_f32_e32 v22, v21, v24
	v_max_f32_e32 v23, v18, v25
	ds_bpermute_b32 v18, v220, v0
	ds_bpermute_b32 v21, v220, v20
	ds_bpermute_b32 v24, v220, v22
	ds_bpermute_b32 v25, v220, v23
	s_waitcnt lgkmcnt(3)
	v_max_f32_e32 v18, v18, v18
	s_waitcnt lgkmcnt(2)
	v_max_f32_e32 v19, v21, v21
	s_waitcnt lgkmcnt(1)
	v_max_f32_e32 v24, v24, v24
	s_waitcnt lgkmcnt(0)
	v_max_f32_e32 v25, v25, v25
	v_max_f32_e32 v21, v0, v18
	v_max_f32_e32 v19, v20, v19
	v_max_f32_e32 v18, v22, v24
	v_max_f32_e32 v0, v23, v25
	ds_bpermute_b32 v24, v221, v21
	ds_bpermute_b32 v23, v221, v19
	ds_bpermute_b32 v22, v221, v18
	ds_bpermute_b32 v20, v221, v0
	s_cbranch_vccnz .LBB0_627
; __global__ void __launch_bounds__(NWAVES * 64, 2) mk_fwd(Args args) {
;     ...
;               float a0 = fabsf(ap->in[7][l * 128 + lane]), a1 = fabsf(ap->in[7][l * 128 + 64 + lane]), d0 = fabsf(ap->in[8][l * 128 + lane]), d1 = fabsf(ap->in[8][l * 128 + 64 + lane]);
; #pragma unroll
;               for (int o = 1; o < 64; o <<= 1) { a0 = fmaxf(a0, __shfl_xor(a0, o)); a1 = fmaxf(a1, __shfl_xor(a1, o)); d0 = fmaxf(d0, __shfl_xor(d0, o)); d1 = fmaxf(d1, __shfl_xor(d1, o)); }
;               nomax_swa = (8.0f * LOG2E * 1.02f * a0 * a1) <= 40.0f; nomax_diff = (8.0f * LOG2E * 1.02f * d0 * d1) <= 40.0f; }
;     ...
;             const float lam_init = 0.8f - 0.6f * expf(-0.3f * (float)l);
;             const float* lp = ap->in[10] + l * 256;
;             const float lam = expf(wave_sum(lp[lane] * lp[64 + lane])) - expf(wave_sum(lp[128 + lane] * lp[192 + lane])) + lam_init;
;             const float* sl = ap->in[11] + l * 128 + (8 * lane & 127);
;             float gsc[8];
; #pragma unroll
;             for (int i = 0; i < 8; ++i) gsc[i] = sl[i] * (1.0f - lam_init);
	s_load_dwordx2 s[54:55], s[46:47], 0x78
	s_waitcnt lgkmcnt(0)
	v_max_f32_e32 v24, v24, v24
	v_max_f32_e32 v21, v21, v21
	v_max_f32_e32 v22, v22, v22
	v_max_f32_e32 v18, v18, v18
	v_max_f32_e32 v21, v21, v24
	v_max_f32_e32 v23, v23, v23
	v_max_f32_e32 v19, v19, v19
	v_max_f32_e32 v18, v18, v22
	v_max_f32_e32 v20, v20, v20
	v_max_f32_e32 v0, v0, v0
	v_max_f32_e32 v19, v19, v23
	v_max_f32_e32 v0, v0, v20
	s_add_u32 s72, s54, 0x2000000
	v_mul_f32_e32 v20, 0x413c5bb7, v21
	v_mul_f32_e32 v18, 0x413c5bb7, v18
	s_addc_u32 s73, s55, 0
	v_mul_f32_e32 v178, v19, v20
	v_mul_f32_e32 v179, v0, v18
	s_load_dwordx2 s[40:41], s[46:47], 0x50
	s_lshl_b32 s2, s78, 10
	s_mov_b32 s3, 0x3fb8aa3b
	v_lshlrev_b32_e32 v18, 2, v215
	s_waitcnt lgkmcnt(0)
	s_add_u32 s40, s40, s2
	s_addc_u32 s41, s41, 0
	global_load_dword v19, v18, s[40:41]
	global_load_dword v20, v18, s[40:41] offset:256
	global_load_dword v21, v18, s[40:41] offset:512
	global_load_dword v22, v18, s[40:41] offset:768
	s_waitcnt vmcnt(2)
	v_mul_f32_e32 v19, v19, v20
	s_waitcnt vmcnt(0)
	v_mul_f32_e32 v21, v21, v22
	ds_bpermute_b32 v20, v187, v19
	ds_bpermute_b32 v22, v187, v21
	s_waitcnt lgkmcnt(0)
	v_add_f32_e32 v19, v19, v20
	v_add_f32_e32 v21, v21, v22
	ds_bpermute_b32 v20, v200, v19
	ds_bpermute_b32 v22, v200, v21
	s_waitcnt lgkmcnt(0)
	v_add_f32_e32 v19, v19, v20
	v_add_f32_e32 v21, v21, v22
	ds_bpermute_b32 v20, v201, v19
	ds_bpermute_b32 v22, v201, v21
	s_waitcnt lgkmcnt(0)
	v_add_f32_e32 v19, v19, v20
	v_add_f32_e32 v21, v21, v22
	ds_bpermute_b32 v20, v202, v19
	ds_bpermute_b32 v22, v202, v21
	s_waitcnt lgkmcnt(0)
	v_add_f32_e32 v19, v19, v20
	v_add_f32_e32 v21, v21, v22
	ds_bpermute_b32 v20, v220, v19
	ds_bpermute_b32 v22, v220, v21
	s_waitcnt lgkmcnt(0)
	v_add_f32_e32 v19, v19, v20
	v_add_f32_e32 v21, v21, v22
	ds_bpermute_b32 v20, v221, v19
	ds_bpermute_b32 v22, v221, v21
	s_waitcnt lgkmcnt(0)
	v_add_f32_e32 v19, v19, v20
	v_add_f32_e32 v21, v21, v22
	v_mul_f32_e32 v23, 0x3fb8aa3b, v19
	v_fma_f32 v24, v19, s3, -v23
	v_rndne_f32_e32 v25, v23
	v_fmac_f32_e32 v24, 0x32a5705f, v19
	v_sub_f32_e32 v23, v23, v25
	v_add_f32_e32 v23, v23, v24
	v_exp_f32_e32 v23, v23
	v_cvt_i32_f32_e32 v25, v25
	s_nop 0
	v_ldexp_f32 v19, v23, v25
	v_mul_f32_e32 v23, 0x3fb8aa3b, v21
	v_fma_f32 v24, v21, s3, -v23
	v_rndne_f32_e32 v25, v23
	v_fmac_f32_e32 v24, 0x32a5705f, v21
	v_sub_f32_e32 v23, v23, v25
	v_add_f32_e32 v23, v23, v24
	v_exp_f32_e32 v23, v23
	v_cvt_i32_f32_e32 v25, v25
	s_nop 0
	v_ldexp_f32 v21, v23, v25
	v_cvt_f32_u32_e32 v22, s78
	v_mul_f32_e32 v22, 0xbe99999a, v22
	v_mul_f32_e32 v23, 0x3fb8aa3b, v22
	v_fma_f32 v24, v22, s3, -v23
	v_rndne_f32_e32 v25, v23
	v_fmac_f32_e32 v24, 0x32a5705f, v22
	v_sub_f32_e32 v23, v23, v25
	v_add_f32_e32 v23, v23, v24
	v_exp_f32_e32 v23, v23
	v_cvt_i32_f32_e32 v25, v25
	s_nop 0
	v_ldexp_f32 v22, v23, v25
	v_mov_b32_e32 v23, 0x3f4ccccd
	v_fmamk_f32 v22, v22, 0xbf19999a, v23
	v_sub_f32_e32 v19, v19, v21
	v_add_f32_e32 v24, v22, v19
	v_sub_f32_e32 v25, 1.0, v22
	v_lshrrev_b32_e32 v26, 6, v212
	v_lshlrev_b32_e32 v26, 3, v26
	v_add_u32_e32 v26, 0x1b000, v26
	ds_write_b64 v26, v[24:25]
	s_waitcnt lgkmcnt(0)
	s_lshl_b32 s74, s70, 3
	s_mov_b64 s[38:39], 0
	v_readlane_b32 s75, v253, 6
	v_mov_b32_e32 v234, v212
	s_branch .LBB0_247

; __device__ __forceinline__ int crow(int r,int hi){return (r&3)+8*(r>>2)+4*hi;}
; template<int THRL> __device__ __forceinline__ void attn_unit(long rowbase,int qb,int t0,bool WIN,bool NOMAX,const bf16*Qc,const bf16*__restrict__ Kc,const bf16*__restrict__ Vc,bf16*Oc,float s2,float sink2,char*shm,
;     bf16x8 (&qr)[4],bool pref,const bf16*qkvb,int vn,int in_){
;     ...
;   if(hi==0)wsf[32+r32]=l_reg;asm volatile("s_waitcnt lgkmcnt(0)":::"memory");
;   float rli[16];
;   #pragma unroll
;   for(int r=0;r<16;++r)rli[r]=__builtin_amdgcn_rcpf(wsf[32+crow(r,hi)]);
;   bf16*Ow=Oc+(rowbase+q0+wid*QBLK)*POUT;
;   { bf16*stg=(bf16*)(shm+LDS_OST)+wid*2048;
;     #pragma unroll
;     for(int r=0;r<16;++r){const int orow=crow(r,hi);
;       #pragma unroll
;       for(int d0=0;d0<2;++d0)stg[orow*64+d0*32+r32]=__float2bfloat16(o[d0][r]*rli[r]);}
;     asm volatile("s_waitcnt lgkmcnt(0)":::"memory");
;     #pragma unroll
;     for(int i=0;i<4;++i){const int row=i*8+(lane>>3),ch=lane&7; const u32x4 v=*(const u32x4*)(stg+row*64+ch*8); ATTN_STORE16(Ow+(long)row*POUT+ch*8,v);} }
; __global__ void __launch_bounds__(NWAVES * 64, 2) mk_fwd(Args args) {
;     ...
;                         const int s = v & 7, bhv = (v >> 3) + 32 * (i >> 2), ii = i & 3, b = bhv >> 4, h = (bhv >> 2) & 3, c = (bhv >> 1) & 1, vh = bhv & 1;
;                         qb = (ii == 0) ? s : (ii == 1) ? 15 - s : (ii == 2) ? 16 + s : 31 - s; t0 = 0; win = false; rowbase = (long)b * SEQ;
;                         qc = 768 + h * 128 + c * 64; kc = 1280 + h * 128 + c * 64; vc = 1792 + h * 128 + vh * 64; oc = h * 128 + vh * 64; Ob = c ? OD1 : OD0;
;                         s2 = exp2f(-8.0f * (float)(9 + h) / 12.0f) * LOG2E; sink2 = -INFINITY;
.LBB0_247:
	s_and_b32 s76, s75, 7
	s_xor_b32 s4, s76, 15
	s_ashr_i32 s77, s75, 3
	v_writelane_b32 v252, s4, 13
	s_or_b32 s4, s76, 16
	s_bfe_u32 s2, s75, 0x20004
	s_bfe_u32 s3, s77, 0x10001
	v_writelane_b32 v252, s4, 15
	s_xor_b32 s4, s76, 31
	v_writelane_b32 v252, s4, 20
	s_lshl_b32 s4, s2, 7
	s_lshl_b32 s33, s3, 6
	s_or_b32 s89, s4, s33
	s_lshl_b32 s33, s77, 6
	s_and_b32 s33, s33, 0
	s_or_b32 s33, s4, s33
	s_add_i32 s88, s89, 0x300
	s_addk_i32 s89, 0x500
	s_add_i32 s91, s33, 0x700
	s_cmp_eq_u32 s3, 0
	s_mov_b32 s3, 0x17000000
	s_cselect_b32 s56, s3, 0x19000000
	s_lshl_b32 s2, s2, 3
	s_xor_b32 s2, s2, 0xffffffb8
	v_cvt_f32_i32_e32 v0, s2
	s_mov_b32 s4, 0x41400000
	s_mov_b32 s57, 0
	s_mov_b32 s85, s57
	v_div_scale_f32 v18, s[2:3], s4, s4, v0
	v_rcp_f32_e32 v19, v18
	s_mov_b32 s2, 0xc2fc0000
	v_fma_f32 v20, -v18, v19, 1.0
	v_fmac_f32_e32 v19, v20, v19
	v_div_scale_f32 v20, vcc, v0, s4, v0
	v_mul_f32_e32 v21, v20, v19
	v_fma_f32 v22, -v18, v21, v20
	v_fmac_f32_e32 v21, v22, v19
	v_fma_f32 v18, -v18, v21, v20
	v_div_fmas_f32 v18, v18, v19, v21
	v_div_fixup_f32 v0, v18, s4, v0
	v_cmp_gt_f32_e32 vcc, s2, v0
	s_and_b64 s[2:3], vcc, exec
	s_cselect_b32 s2, 0xffffffc0, 0
	v_cndmask_b32_e32 v18, 0, v216, vcc
	v_add_f32_e32 v0, v0, v18
	v_exp_f32_e32 v0, v0
	s_lshl_b32 s3, s75, 2
	s_add_i32 s3, s3, -8
	v_ldexp_f32 v182, v0, s2
	s_branch .LBB0_249
.LBB0_248:
	s_or_b64 exec, exec, s[42:43]
	s_waitcnt lgkmcnt(0)
	ds_read_b128 v[50:53], v227 offset:49280
	ds_read_b128 v[54:57], v227 offset:49312
	s_add_u32 s2, s54, s52
	s_addc_u32 s4, s55, s53
	s_lshl_b32 s42, s90, 1
	s_waitcnt lgkmcnt(1)
	v_rcp_f32_e32 v0, v50
	s_add_u32 s2, s2, s42
	v_rcp_f32_e32 v58, v51
	s_addc_u32 s4, s4, 0
	s_lshl_b32 s44, s80, 12
	s_add_i32 s44, s44, 0
	v_lshlrev_b32_e32 v65, 1, v180
	v_lshlrev_b32_e32 v66, 9, v181
	v_mul_f32_e32 v18, v18, v0
	v_mul_f32_e32 v0, v34, v0
	v_add3_u32 v65, s44, v65, v66
	v_cvt_pk_bf16_f32 v0, v0, s0
	v_rcp_f32_e32 v59, v52
	v_rcp_f32_e32 v60, v53
	s_waitcnt lgkmcnt(0)
	v_rcp_f32_e32 v61, v54
	ds_read_b128 v[50:53], v227 offset:49344
	v_rcp_f32_e32 v62, v55
	v_rcp_f32_e32 v63, v56
	v_rcp_f32_e32 v64, v57
	ds_read_b128 v[54:57], v227 offset:49376
	ds_write_b16 v65, v0 offset:51264
	v_mul_f32_e32 v0, v19, v58
	v_cvt_pk_bf16_f32 v0, v0, s0
	ds_write_b16 v65, v0 offset:51328
	v_mul_f32_e32 v0, v35, v58
	v_cvt_pk_bf16_f32 v0, v0, s0
	ds_write_b16 v65, v0 offset:51392
	v_mul_f32_e32 v0, v20, v59
	v_cvt_pk_bf16_f32 v0, v0, s0
	ds_write_b16 v65, v0 offset:51456
	v_mul_f32_e32 v0, v36, v59
	v_cvt_pk_bf16_f32 v0, v0, s0
	ds_write_b16 v65, v0 offset:51520
	v_mul_f32_e32 v0, v21, v60
	v_cvt_pk_bf16_f32 v0, v0, s0
	ds_write_b16 v65, v0 offset:51584
	v_mul_f32_e32 v0, v37, v60
	v_cvt_pk_bf16_f32 v0, v0, s0
	ds_write_b16 v65, v0 offset:51648
	v_mul_f32_e32 v0, v22, v61
	v_cvt_pk_bf16_f32 v0, v0, s0
	ds_write_b16 v65, v0 offset:52224
	v_mul_f32_e32 v0, v38, v61
	v_cvt_pk_bf16_f32 v0, v0, s0
	ds_write_b16 v65, v0 offset:52288
	v_mul_f32_e32 v0, v23, v62
	v_cvt_pk_bf16_f32 v0, v0, s0
	ds_write_b16 v65, v0 offset:52352
	v_mul_f32_e32 v0, v39, v62
	v_cvt_pk_bf16_f32 v0, v0, s0
	ds_write_b16 v65, v0 offset:52416
	v_mul_f32_e32 v0, v24, v63
	v_cvt_pk_bf16_f32 v0, v0, s0
	ds_write_b16 v65, v0 offset:52480
	v_mul_f32_e32 v0, v40, v63
	v_cvt_pk_bf16_f32 v0, v0, s0
	s_waitcnt lgkmcnt(13)
	v_rcp_f32_e32 v50, v50
	ds_write_b16 v65, v0 offset:52544
	v_mul_f32_e32 v0, v25, v64
	v_cvt_pk_bf16_f32 v0, v0, s0
	ds_write_b16 v65, v0 offset:52608
	v_mul_f32_e32 v0, v41, v64
	v_cvt_pk_bf16_f32 v0, v0, s0
	v_rcp_f32_e32 v51, v51
	ds_write_b16 v65, v0 offset:52672
	v_mul_f32_e32 v0, v26, v50
	v_cvt_pk_bf16_f32 v0, v0, s0
	ds_write_b16 v65, v0 offset:53248
	v_mul_f32_e32 v0, v42, v50
	v_cvt_pk_bf16_f32 v0, v0, s0
	v_rcp_f32_e32 v52, v52
	ds_write_b16 v65, v0 offset:53312
	v_mul_f32_e32 v0, v27, v51
	v_cvt_pk_bf16_f32 v0, v0, s0
	ds_write_b16 v65, v0 offset:53376
	v_mul_f32_e32 v0, v43, v51
	v_cvt_pk_bf16_f32 v0, v0, s0
	v_rcp_f32_e32 v53, v53
	ds_write_b16 v65, v0 offset:53440
	v_mul_f32_e32 v0, v28, v52
	v_cvt_pk_bf16_f32 v0, v0, s0
	ds_write_b16 v65, v0 offset:53504
	v_mul_f32_e32 v0, v44, v52
	v_cvt_pk_bf16_f32 v0, v0, s0
	s_waitcnt lgkmcnt(14)
	v_rcp_f32_e32 v54, v54
	ds_write_b16 v65, v0 offset:53568
	v_mul_f32_e32 v0, v29, v53
	v_cvt_pk_bf16_f32 v0, v0, s0
	ds_write_b16 v65, v0 offset:53632
	v_mul_f32_e32 v0, v45, v53
	v_cvt_pk_bf16_f32 v0, v0, s0
	v_rcp_f32_e32 v55, v55
	ds_write_b16 v65, v0 offset:53696
	v_mul_f32_e32 v0, v30, v54
	v_cvt_pk_bf16_f32 v0, v0, s0
	ds_write_b16 v65, v0 offset:54272
	v_mul_f32_e32 v0, v46, v54
	v_cvt_pk_bf16_f32 v0, v0, s0
	v_rcp_f32_e32 v56, v56
	ds_write_b16 v65, v0 offset:54336
	v_mul_f32_e32 v0, v31, v55
	v_cvt_pk_bf16_f32 v0, v0, s0
	ds_write_b16 v65, v0 offset:54400
	v_mul_f32_e32 v0, v47, v55
	v_cvt_pk_bf16_f32 v0, v0, s0
	v_rcp_f32_e32 v57, v57
	ds_write_b16 v65, v0 offset:54464
	v_mul_f32_e32 v0, v32, v56
	v_cvt_pk_bf16_f32 v0, v0, s0
	ds_write_b16 v65, v0 offset:54528
	v_mul_f32_e32 v0, v48, v56
	v_cvt_pk_bf16_f32 v0, v0, s0
	ds_write_b16 v65, v0 offset:54592
	v_mul_f32_e32 v0, v33, v57
	v_cvt_pk_bf16_f32 v0, v0, s0
	ds_write_b16 v65, v0 offset:54656
	v_mul_f32_e32 v0, v49, v57
	v_cvt_pk_bf16_f32 v0, v0, s0
	s_lshl_b64 s[42:43], s[58:59], 10
	ds_write_b16 v65, v0 offset:54720
	v_lshlrev_b32_e32 v0, 1, v233
	v_cvt_pk_bf16_f32 v18, v18, s0
	s_add_u32 s42, s2, s42
	v_and_b32_e32 v0, 0x70, v0
	ds_write_b16 v65, v18 offset:51200
	s_addc_u32 s43, s4, s43
	v_lshrrev_b32_e32 v30, 3, v183
	v_add_u32_e32 v31, s44, v0
	s_waitcnt lgkmcnt(0)
	v_lshl_add_u64 v[26:27], s[42:43], 0, v[0:1]
	v_lshl_add_u32 v0, v30, 7, v31
	v_or_b32_e32 v32, 8, v30
	ds_read_b128 v[18:21], v0 offset:51200
	v_lshl_add_u32 v22, v32, 7, v31
	ds_read_b128 v[22:25], v22 offset:51200
	v_lshlrev_b32_e32 v0, 10, v30
	v_lshl_add_u64 v[28:29], v[26:27], 0, v[0:1]
	v_lshlrev_b32_e32 v0, 10, v32
	s_waitcnt lgkmcnt(1)
	global_store_dwordx4 v[28:29], v[18:21], off
	s_and_b64 vcc, s[40:41], exec
	s_nop 0
	v_lshl_add_u64 v[18:19], v[26:27], 0, v[0:1]
	v_or_b32_e32 v0, 16, v30
	s_waitcnt lgkmcnt(0)
	global_store_dwordx4 v[18:19], v[22:25], off
	v_lshl_add_u32 v18, v0, 7, v31
	v_or_b32_e32 v30, 24, v30
	ds_read_b128 v[18:21], v18 offset:51200
	v_lshl_add_u32 v22, v30, 7, v31
	ds_read_b128 v[22:25], v22 offset:51200
	v_lshlrev_b32_e32 v0, 10, v0
	v_lshl_add_u64 v[28:29], v[26:27], 0, v[0:1]
	v_lshlrev_b32_e32 v0, 10, v30
	s_waitcnt lgkmcnt(1)
	global_store_dwordx4 v[28:29], v[18:21], off
	s_nop 1
	v_lshl_add_u64 v[18:19], v[26:27], 0, v[0:1]
	s_waitcnt lgkmcnt(0)
	global_store_dwordx4 v[18:19], v[22:25], off
	s_cmp_gt_u32 s85, 8
	s_cbranch_scc1 .Lmy_epi_skip
; __device__ __forceinline__ int crow(int r,int hi){return (r&3)+8*(r>>2)+4*hi;}
; template<int THRL> __device__ __forceinline__ void attn_unit(long rowbase,int qb,int t0,bool WIN,bool NOMAX,const bf16*Qc,const bf16*__restrict__ Kc,const bf16*__restrict__ Vc,bf16*Oc,float s2,float sink2,char*shm,
;     bf16x8 (&qr)[4],bool pref,const bf16*qkvb,int vn,int in_){
;     ...
;   if(hi==0)wsf[32+r32]=l_reg;asm volatile("s_waitcnt lgkmcnt(0)":::"memory");
;   float rli[16];
;   #pragma unroll
;   for(int r=0;r<16;++r)rli[r]=__builtin_amdgcn_rcpf(wsf[32+crow(r,hi)]);
;   bf16*Ow=Oc+(rowbase+q0+wid*QBLK)*POUT;
;   { bf16*stg=(bf16*)(shm+LDS_OST)+wid*2048;
;     #pragma unroll
;     for(int r=0;r<16;++r){const int orow=crow(r,hi);
;       #pragma unroll
;       for(int d0=0;d0<2;++d0)stg[orow*64+d0*32+r32]=__float2bfloat16(o[d0][r]*rli[r]);}
;     asm volatile("s_waitcnt lgkmcnt(0)":::"memory");
;     #pragma unroll
;     for(int i=0;i<4;++i){const int row=i*8+(lane>>3),ch=lane&7; const u32x4 v=*(const u32x4*)(stg+row*64+ch*8); ATTN_STORE16(Ow+(long)row*POUT+ch*8,v);} }
	ds_read_b128 v[50:53], v227 offset:49280
	ds_read_b128 v[54:57], v227 offset:49312
	s_add_u32 s2, s54, s52
	s_addc_u32 s4, s55, s53
	s_lshl_b32 s42, s90, 1
	s_waitcnt lgkmcnt(1)
	v_rcp_f32_e32 v0, v50
	s_add_u32 s2, s2, s42
	v_rcp_f32_e32 v58, v51
	s_addc_u32 s4, s4, 0
	s_lshl_b32 s44, s80, 12
	s_add_i32 s44, s44, 0
	v_lshlrev_b32_e32 v65, 1, v180
	v_lshlrev_b32_e32 v66, 9, v181
	v_mul_f32_e32 v236, v236, v0
	v_mul_f32_e32 v0, v200, v0
	v_add3_u32 v65, s44, v65, v66
	v_cvt_pk_bf16_f32 v0, v0, s0
	v_rcp_f32_e32 v59, v52
	v_rcp_f32_e32 v60, v53
	s_waitcnt lgkmcnt(0)
	v_rcp_f32_e32 v61, v54
	ds_read_b128 v[50:53], v227 offset:49344
	v_rcp_f32_e32 v62, v55
	v_rcp_f32_e32 v63, v56
	v_rcp_f32_e32 v64, v57
	ds_read_b128 v[54:57], v227 offset:49376
	ds_write_b16 v65, v0 offset:51264
	v_mul_f32_e32 v0, v237, v58
	v_cvt_pk_bf16_f32 v0, v0, s0
	ds_write_b16 v65, v0 offset:51328
	v_mul_f32_e32 v0, v201, v58
	v_cvt_pk_bf16_f32 v0, v0, s0
	ds_write_b16 v65, v0 offset:51392
	v_mul_f32_e32 v0, v238, v59
	v_cvt_pk_bf16_f32 v0, v0, s0
	ds_write_b16 v65, v0 offset:51456
	v_mul_f32_e32 v0, v202, v59
	v_cvt_pk_bf16_f32 v0, v0, s0
	ds_write_b16 v65, v0 offset:51520
	v_mul_f32_e32 v0, v239, v60
	v_cvt_pk_bf16_f32 v0, v0, s0
	ds_write_b16 v65, v0 offset:51584
	v_mul_f32_e32 v0, v203, v60
	v_cvt_pk_bf16_f32 v0, v0, s0
	ds_write_b16 v65, v0 offset:51648
	v_mul_f32_e32 v0, v240, v61
	v_cvt_pk_bf16_f32 v0, v0, s0
	ds_write_b16 v65, v0 offset:52224
	v_mul_f32_e32 v0, v204, v61
	v_cvt_pk_bf16_f32 v0, v0, s0
	ds_write_b16 v65, v0 offset:52288
	v_mul_f32_e32 v0, v241, v62
	v_cvt_pk_bf16_f32 v0, v0, s0
	ds_write_b16 v65, v0 offset:52352
	v_mul_f32_e32 v0, v205, v62
	v_cvt_pk_bf16_f32 v0, v0, s0
	ds_write_b16 v65, v0 offset:52416
	v_mul_f32_e32 v0, v242, v63
	v_cvt_pk_bf16_f32 v0, v0, s0
	ds_write_b16 v65, v0 offset:52480
	v_mul_f32_e32 v0, v206, v63
	v_cvt_pk_bf16_f32 v0, v0, s0
	s_waitcnt lgkmcnt(13)
	v_rcp_f32_e32 v50, v50
	ds_write_b16 v65, v0 offset:52544
	v_mul_f32_e32 v0, v243, v64
	v_cvt_pk_bf16_f32 v0, v0, s0
	ds_write_b16 v65, v0 offset:52608
	v_mul_f32_e32 v0, v207, v64
	v_cvt_pk_bf16_f32 v0, v0, s0
	v_rcp_f32_e32 v51, v51
	ds_write_b16 v65, v0 offset:52672
	v_mul_f32_e32 v0, v244, v50
	v_cvt_pk_bf16_f32 v0, v0, s0
	ds_write_b16 v65, v0 offset:53248
	v_mul_f32_e32 v0, v208, v50
	v_cvt_pk_bf16_f32 v0, v0, s0
	v_rcp_f32_e32 v52, v52
	ds_write_b16 v65, v0 offset:53312
	v_mul_f32_e32 v0, v245, v51
	v_cvt_pk_bf16_f32 v0, v0, s0
	ds_write_b16 v65, v0 offset:53376
	v_mul_f32_e32 v0, v209, v51
	v_cvt_pk_bf16_f32 v0, v0, s0
	v_rcp_f32_e32 v53, v53
	ds_write_b16 v65, v0 offset:53440
	v_mul_f32_e32 v0, v246, v52
	v_cvt_pk_bf16_f32 v0, v0, s0
	ds_write_b16 v65, v0 offset:53504
	v_mul_f32_e32 v0, v210, v52
	v_cvt_pk_bf16_f32 v0, v0, s0
	s_waitcnt lgkmcnt(14)
	v_rcp_f32_e32 v54, v54
	ds_write_b16 v65, v0 offset:53568
	v_mul_f32_e32 v0, v247, v53
	v_cvt_pk_bf16_f32 v0, v0, s0
	ds_write_b16 v65, v0 offset:53632
	v_mul_f32_e32 v0, v211, v53
	v_cvt_pk_bf16_f32 v0, v0, s0
	v_rcp_f32_e32 v55, v55
	ds_write_b16 v65, v0 offset:53696
	v_mul_f32_e32 v0, v248, v54
	v_cvt_pk_bf16_f32 v0, v0, s0
	ds_write_b16 v65, v0 offset:54272
	v_mul_f32_e32 v0, v212, v54
	v_cvt_pk_bf16_f32 v0, v0, s0
	v_rcp_f32_e32 v56, v56
	ds_write_b16 v65, v0 offset:54336
	v_mul_f32_e32 v0, v249, v55
	v_cvt_pk_bf16_f32 v0, v0, s0
	ds_write_b16 v65, v0 offset:54400
	v_mul_f32_e32 v0, v213, v55
	v_cvt_pk_bf16_f32 v0, v0, s0
	v_rcp_f32_e32 v57, v57
	ds_write_b16 v65, v0 offset:54464
	v_mul_f32_e32 v0, v250, v56
	v_cvt_pk_bf16_f32 v0, v0, s0
	ds_write_b16 v65, v0 offset:54528
	v_mul_f32_e32 v0, v214, v56
	v_cvt_pk_bf16_f32 v0, v0, s0
	ds_write_b16 v65, v0 offset:54592
	v_mul_f32_e32 v0, v251, v57
	v_cvt_pk_bf16_f32 v0, v0, s0
	ds_write_b16 v65, v0 offset:54656
	v_mul_f32_e32 v0, v215, v57
	v_cvt_pk_bf16_f32 v0, v0, s0
	s_lshl_b64 s[42:43], s[58:59], 10
	ds_write_b16 v65, v0 offset:54720
	v_lshlrev_b32_e32 v0, 1, v233
	v_cvt_pk_bf16_f32 v236, v236, s0
	s_add_u32 s42, s2, s42
	v_and_b32_e32 v0, 0x70, v0
	ds_write_b16 v65, v236 offset:51200
	s_addc_u32 s43, s4, s43
	s_add_u32 s42, s42, 0x80
	s_addc_u32 s43, s43, 0
	v_lshrrev_b32_e32 v248, 3, v183
	v_add_u32_e32 v249, s44, v0
	s_waitcnt lgkmcnt(0)
	v_lshl_add_u64 v[244:245], s[42:43], 0, v[0:1]
	v_lshl_add_u32 v0, v248, 7, v249
	v_or_b32_e32 v250, 8, v248
	ds_read_b128 v[236:239], v0 offset:51200
	v_lshl_add_u32 v240, v250, 7, v249
	ds_read_b128 v[240:243], v240 offset:51200
	v_lshlrev_b32_e32 v0, 10, v248
	v_lshl_add_u64 v[246:247], v[244:245], 0, v[0:1]
	v_lshlrev_b32_e32 v0, 10, v250
	s_waitcnt lgkmcnt(1)
	global_store_dwordx4 v[246:247], v[236:239], off
	s_and_b64 vcc, s[40:41], exec
	s_nop 0
	v_lshl_add_u64 v[236:237], v[244:245], 0, v[0:1]
	v_or_b32_e32 v0, 16, v248
	s_waitcnt lgkmcnt(0)
	global_store_dwordx4 v[236:237], v[240:243], off
	v_lshl_add_u32 v236, v0, 7, v249
	v_or_b32_e32 v248, 24, v248
	ds_read_b128 v[236:239], v236 offset:51200
	v_lshl_add_u32 v240, v248, 7, v249
	ds_read_b128 v[240:243], v240 offset:51200
	v_lshlrev_b32_e32 v0, 10, v0
	v_lshl_add_u64 v[246:247], v[244:245], 0, v[0:1]
	v_lshlrev_b32_e32 v0, 10, v248
	s_waitcnt lgkmcnt(1)
	global_store_dwordx4 v[246:247], v[236:239], off
	s_nop 1
	v_lshl_add_u64 v[236:237], v[244:245], 0, v[0:1]
	s_waitcnt lgkmcnt(0)
	global_store_dwordx4 v[236:237], v[240:243], off
	s_cmp_eq_u32 s85, 2
	s_cbranch_scc1 .Lmy_comb
	s_cmp_lg_u32 s85, 8
	s_cbranch_scc1 .Lmy_epi_skip
; #define GAS __attribute__((address_space(1)))
; __device__ __forceinline__ unsigned pk2(float lo, float hi) { return f2bf(lo) | (f2bf(hi) << 16); }
; #define KARGS() ({ kargs_t p_ = (kargs_t)__builtin_amdgcn_kernarg_segment_ptr(); asm volatile("" : "+s"(p_)); p_; })
; __global__ void __launch_bounds__(NWAVES * 64, 2) mk_fwd(Args args) {
;     ...
;             kargs_t ap = KARGS(); bf16* OD0 = WSP(bf16, WS_OD0); bf16* OD1 = WSP(bf16, WS_OD1); bf16* OB = WSP(bf16, WS_OB);
;             const float lam_init = 0.8f - 0.6f * expf(-0.3f * (float)l);
;             const float* lp = ap->in[10] + l * 256;
;             const float lam = expf(wave_sum(lp[lane] * lp[64 + lane])) - expf(wave_sum(lp[128 + lane] * lp[192 + lane])) + lam_init;
;             const float* sl = ap->in[11] + l * 128 + (8 * lane & 127);
;             float gsc[8];
; #pragma unroll
;             for (int i = 0; i < 8; ++i) gsc[i] = sl[i] * (1.0f - lam_init);
;             for (int m0 = gw; m0 < M; m0 += 4 * NGW) {
;                 v4u a[4], b[4];
; #pragma unroll
;                 for (int j = 0; j < 4; ++j) { const int m = m0 + j * NGW; if (m < M) { a[j] = *(const GAS v4u*)(OD0 + (size_t)m * 512 + 8 * lane); b[j] = *(const GAS v4u*)(OD1 + (size_t)m * 512 + 8 * lane); } else { a[j] = (v4u){0u, 0u, 0u, 0u}; b[j] = a[j]; } }
; #pragma unroll
;                 for (int j = 0; j < 4; ++j) { const int m = m0 + j * NGW;
;                     float o[8];
; #pragma unroll
;                     for (int i = 0; i < 4; ++i) { o[2 * i] = __uint_as_float(a[j][i] << 16) - lam * __uint_as_float(b[j][i] << 16); o[2 * i + 1] = __uint_as_float(a[j][i] & 0xffff0000u) - lam * __uint_as_float(b[j][i] & 0xffff0000u); }
;                     float ss = 0.f;
; #pragma unroll
;                     for (int i = 0; i < 8; ++i) ss += o[i] * o[i];
;                     ss += __shfl_xor(ss, 1); ss += __shfl_xor(ss, 2); ss += __shfl_xor(ss, 4); ss += __shfl_xor(ss, 8);
;                     const float rn = __builtin_amdgcn_rsqf(ss * (1.0f / 128.0f) + 1e-6f);
;                     v4u w;
; #pragma unroll
;                     for (int i = 0; i < 4; ++i) w[i] = pk2(o[2 * i] * rn * gsc[2 * i], o[2 * i + 1] * rn * gsc[2 * i + 1]);
;                     if (m < M) *(GAS v4u*)(OB + (size_t)m * 512 + 8 * lane) = w; }
.Lmy_comb:
	s_waitcnt vmcnt(0)
	v_lshrrev_b32_e32 v50, 6, v234
	v_lshlrev_b32_e32 v50, 3, v50
	v_add_u32_e32 v50, 0x1b000, v50
	ds_read_b64 v[50:51], v50
	v_and_b32_e32 v52, 15, v183
	v_lshrrev_b32_e32 v53, 4, v183
	v_lshlrev_b32_e32 v52, 4, v52
	v_lshl_add_u32 v53, v53, 10, v52
	s_load_dwordx2 s[100:101], s[46:47], 0x58
	s_lshl_b32 s4, s78, 9
	v_lshlrev_b32_e32 v52, 1, v52
	s_waitcnt lgkmcnt(0)
	s_add_u32 s100, s100, s4
	s_addc_u32 s101, s101, 0
	global_load_dwordx4 v[54:57], v52, s[100:101]
	global_load_dwordx4 v[58:61], v52, s[100:101] offset:16
	s_lshl_b64 s[42:43], s[58:59], 10
	s_add_u32 s42, s42, s54
	s_addc_u32 s43, s43, s55
	s_lshl_b32 s44, s90, 1
	s_add_u32 s42, s42, s44
	s_addc_u32 s43, s43, 0
	s_add_u32 s100, s42, 0x17000000
	s_addc_u32 s101, s43, 0
	s_add_u32 s44, s42, 0x19000000
	s_addc_u32 s45, s43, 0
	s_add_u32 s42, s42, 0x15000000
	s_addc_u32 s43, s43, 0
	global_load_dwordx4 v[62:65], v53, s[100:101]
	global_load_dwordx4 v[94:97], v53, s[44:45]
	v_add_u32_e32 v126, 0x1000, v53
	global_load_dwordx4 v[66:69], v126, s[100:101]
	global_load_dwordx4 v[98:101], v126, s[44:45]
	v_add_u32_e32 v126, 0x2000, v53
	global_load_dwordx4 v[70:73], v126, s[100:101]
	global_load_dwordx4 v[102:105], v126, s[44:45]
	v_add_u32_e32 v126, 0x3000, v53
	global_load_dwordx4 v[74:77], v126, s[100:101]
	global_load_dwordx4 v[106:109], v126, s[44:45]
	v_add_u32_e32 v126, 0x4000, v53
	global_load_dwordx4 v[78:81], v126, s[100:101]
	global_load_dwordx4 v[110:113], v126, s[44:45]
	v_add_u32_e32 v126, 0x5000, v53
	global_load_dwordx4 v[82:85], v126, s[100:101]
	global_load_dwordx4 v[114:117], v126, s[44:45]
	v_add_u32_e32 v126, 0x6000, v53
	global_load_dwordx4 v[86:89], v126, s[100:101]
	global_load_dwordx4 v[118:121], v126, s[44:45]
	v_add_u32_e32 v126, 0x7000, v53
	global_load_dwordx4 v[90:93], v126, s[100:101]
	global_load_dwordx4 v[122:125], v126, s[44:45]
	s_waitcnt vmcnt(0)
	v_mul_f32_e32 v54, v54, v51
	v_mul_f32_e32 v55, v55, v51
	v_mul_f32_e32 v56, v56, v51
	v_mul_f32_e32 v57, v57, v51
	v_mul_f32_e32 v58, v58, v51
	v_mul_f32_e32 v59, v59, v51
	v_mul_f32_e32 v60, v60, v51
	v_mul_f32_e32 v61, v61, v51
	s_mov_b32 s4, 0xffff0000
	v_lshlrev_b32_e32 v26, 16, v62
	v_and_b32_e32 v27, s4, v62
	v_lshlrev_b32_e32 v28, 16, v94
	v_and_b32_e32 v29, s4, v94
	v_fma_f32 v62, -v50, v28, v26
	v_fma_f32 v94, -v50, v29, v27
	v_lshlrev_b32_e32 v26, 16, v63
	v_and_b32_e32 v27, s4, v63
	v_lshlrev_b32_e32 v28, 16, v95
	v_and_b32_e32 v29, s4, v95
	v_fma_f32 v63, -v50, v28, v26
	v_fma_f32 v95, -v50, v29, v27
	v_lshlrev_b32_e32 v26, 16, v64
	v_and_b32_e32 v27, s4, v64
	v_lshlrev_b32_e32 v28, 16, v96
	v_and_b32_e32 v29, s4, v96
	v_fma_f32 v64, -v50, v28, v26
	v_fma_f32 v96, -v50, v29, v27
	v_lshlrev_b32_e32 v26, 16, v65
	v_and_b32_e32 v27, s4, v65
	v_lshlrev_b32_e32 v28, 16, v97
	v_and_b32_e32 v29, s4, v97
	v_fma_f32 v65, -v50, v28, v26
	v_fma_f32 v97, -v50, v29, v27
	v_mul_f32_e32 v18, v62, v62
	v_fmac_f32_e32 v18, v94, v94
	v_fmac_f32_e32 v18, v63, v63
	v_fmac_f32_e32 v18, v95, v95
	v_fmac_f32_e32 v18, v64, v64
	v_fmac_f32_e32 v18, v96, v96
	v_fmac_f32_e32 v18, v65, v65
	v_fmac_f32_e32 v18, v97, v97
	v_lshlrev_b32_e32 v26, 16, v66
	v_and_b32_e32 v27, s4, v66
	v_lshlrev_b32_e32 v28, 16, v98
	v_and_b32_e32 v29, s4, v98
	v_fma_f32 v66, -v50, v28, v26
	v_fma_f32 v98, -v50, v29, v27
	v_lshlrev_b32_e32 v26, 16, v67
	v_and_b32_e32 v27, s4, v67
	v_lshlrev_b32_e32 v28, 16, v99
	v_and_b32_e32 v29, s4, v99
	v_fma_f32 v67, -v50, v28, v26
	v_fma_f32 v99, -v50, v29, v27
	v_lshlrev_b32_e32 v26, 16, v68
	v_and_b32_e32 v27, s4, v68
	v_lshlrev_b32_e32 v28, 16, v100
	v_and_b32_e32 v29, s4, v100
	v_fma_f32 v68, -v50, v28, v26
	v_fma_f32 v100, -v50, v29, v27
	v_lshlrev_b32_e32 v26, 16, v69
	v_and_b32_e32 v27, s4, v69
	v_lshlrev_b32_e32 v28, 16, v101
	v_and_b32_e32 v29, s4, v101
	v_fma_f32 v69, -v50, v28, v26
	v_fma_f32 v101, -v50, v29, v27
	v_mul_f32_e32 v19, v66, v66
	v_fmac_f32_e32 v19, v98, v98
	v_fmac_f32_e32 v19, v67, v67
	v_fmac_f32_e32 v19, v99, v99
	v_fmac_f32_e32 v19, v68, v68
	v_fmac_f32_e32 v19, v100, v100
	v_fmac_f32_e32 v19, v69, v69
	v_fmac_f32_e32 v19, v101, v101
	v_lshlrev_b32_e32 v26, 16, v70
	v_and_b32_e32 v27, s4, v70
	v_lshlrev_b32_e32 v28, 16, v102
	v_and_b32_e32 v29, s4, v102
	v_fma_f32 v70, -v50, v28, v26
	v_fma_f32 v102, -v50, v29, v27
	v_lshlrev_b32_e32 v26, 16, v71
	v_and_b32_e32 v27, s4, v71
	v_lshlrev_b32_e32 v28, 16, v103
	v_and_b32_e32 v29, s4, v103
	v_fma_f32 v71, -v50, v28, v26
	v_fma_f32 v103, -v50, v29, v27
	v_lshlrev_b32_e32 v26, 16, v72
	v_and_b32_e32 v27, s4, v72
	v_lshlrev_b32_e32 v28, 16, v104
	v_and_b32_e32 v29, s4, v104
	v_fma_f32 v72, -v50, v28, v26
	v_fma_f32 v104, -v50, v29, v27
	v_lshlrev_b32_e32 v26, 16, v73
	v_and_b32_e32 v27, s4, v73
	v_lshlrev_b32_e32 v28, 16, v105
	v_and_b32_e32 v29, s4, v105
	v_fma_f32 v73, -v50, v28, v26
	v_fma_f32 v105, -v50, v29, v27
	v_mul_f32_e32 v20, v70, v70
	v_fmac_f32_e32 v20, v102, v102
	v_fmac_f32_e32 v20, v71, v71
	v_fmac_f32_e32 v20, v103, v103
	v_fmac_f32_e32 v20, v72, v72
	v_fmac_f32_e32 v20, v104, v104
	v_fmac_f32_e32 v20, v73, v73
	v_fmac_f32_e32 v20, v105, v105
	v_lshlrev_b32_e32 v26, 16, v74
	v_and_b32_e32 v27, s4, v74
	v_lshlrev_b32_e32 v28, 16, v106
	v_and_b32_e32 v29, s4, v106
	v_fma_f32 v74, -v50, v28, v26
	v_fma_f32 v106, -v50, v29, v27
	v_lshlrev_b32_e32 v26, 16, v75
	v_and_b32_e32 v27, s4, v75
	v_lshlrev_b32_e32 v28, 16, v107
	v_and_b32_e32 v29, s4, v107
	v_fma_f32 v75, -v50, v28, v26
	v_fma_f32 v107, -v50, v29, v27
	v_lshlrev_b32_e32 v26, 16, v76
	v_and_b32_e32 v27, s4, v76
	v_lshlrev_b32_e32 v28, 16, v108
	v_and_b32_e32 v29, s4, v108
	v_fma_f32 v76, -v50, v28, v26
	v_fma_f32 v108, -v50, v29, v27
; __global__ void __launch_bounds__(NWAVES * 64, 2) mk_fwd(Args args) {
;     ...
;                     for (int i = 0; i < 4; ++i) { o[2 * i] = __uint_as_float(a[j][i] << 16) - lam * __uint_as_float(b[j][i] << 16); o[2 * i + 1] = __uint_as_float(a[j][i] & 0xffff0000u) - lam * __uint_as_float(b[j][i] & 0xffff0000u); }
;                     float ss = 0.f;
; #pragma unroll
;                     for (int i = 0; i < 8; ++i) ss += o[i] * o[i];
;                     ss += __shfl_xor(ss, 1); ss += __shfl_xor(ss, 2); ss += __shfl_xor(ss, 4); ss += __shfl_xor(ss, 8);
	v_lshlrev_b32_e32 v26, 16, v77
	v_and_b32_e32 v27, s4, v77
	v_lshlrev_b32_e32 v28, 16, v109
	v_and_b32_e32 v29, s4, v109
	v_fma_f32 v77, -v50, v28, v26
	v_fma_f32 v109, -v50, v29, v27
	v_mul_f32_e32 v21, v74, v74
	v_fmac_f32_e32 v21, v106, v106
	v_fmac_f32_e32 v21, v75, v75
	v_fmac_f32_e32 v21, v107, v107
	v_fmac_f32_e32 v21, v76, v76
	v_fmac_f32_e32 v21, v108, v108
	v_fmac_f32_e32 v21, v77, v77
	v_fmac_f32_e32 v21, v109, v109
	v_lshlrev_b32_e32 v26, 16, v78
	v_and_b32_e32 v27, s4, v78
	v_lshlrev_b32_e32 v28, 16, v110
	v_and_b32_e32 v29, s4, v110
	v_fma_f32 v78, -v50, v28, v26
	v_fma_f32 v110, -v50, v29, v27
	v_lshlrev_b32_e32 v26, 16, v79
	v_and_b32_e32 v27, s4, v79
	v_lshlrev_b32_e32 v28, 16, v111
	v_and_b32_e32 v29, s4, v111
	v_fma_f32 v79, -v50, v28, v26
	v_fma_f32 v111, -v50, v29, v27
	v_lshlrev_b32_e32 v26, 16, v80
	v_and_b32_e32 v27, s4, v80
	v_lshlrev_b32_e32 v28, 16, v112
	v_and_b32_e32 v29, s4, v112
	v_fma_f32 v80, -v50, v28, v26
	v_fma_f32 v112, -v50, v29, v27
	v_lshlrev_b32_e32 v26, 16, v81
	v_and_b32_e32 v27, s4, v81
	v_lshlrev_b32_e32 v28, 16, v113
	v_and_b32_e32 v29, s4, v113
	v_fma_f32 v81, -v50, v28, v26
	v_fma_f32 v113, -v50, v29, v27
	v_mul_f32_e32 v22, v78, v78
	v_fmac_f32_e32 v22, v110, v110
	v_fmac_f32_e32 v22, v79, v79
	v_fmac_f32_e32 v22, v111, v111
	v_fmac_f32_e32 v22, v80, v80
	v_fmac_f32_e32 v22, v112, v112
	v_fmac_f32_e32 v22, v81, v81
	v_fmac_f32_e32 v22, v113, v113
	v_lshlrev_b32_e32 v26, 16, v82
	v_and_b32_e32 v27, s4, v82
	v_lshlrev_b32_e32 v28, 16, v114
	v_and_b32_e32 v29, s4, v114
	v_fma_f32 v82, -v50, v28, v26
	v_fma_f32 v114, -v50, v29, v27
	v_lshlrev_b32_e32 v26, 16, v83
	v_and_b32_e32 v27, s4, v83
	v_lshlrev_b32_e32 v28, 16, v115
	v_and_b32_e32 v29, s4, v115
	v_fma_f32 v83, -v50, v28, v26
	v_fma_f32 v115, -v50, v29, v27
	v_lshlrev_b32_e32 v26, 16, v84
	v_and_b32_e32 v27, s4, v84
	v_lshlrev_b32_e32 v28, 16, v116
	v_and_b32_e32 v29, s4, v116
	v_fma_f32 v84, -v50, v28, v26
	v_fma_f32 v116, -v50, v29, v27
	v_lshlrev_b32_e32 v26, 16, v85
	v_and_b32_e32 v27, s4, v85
	v_lshlrev_b32_e32 v28, 16, v117
	v_and_b32_e32 v29, s4, v117
	v_fma_f32 v85, -v50, v28, v26
	v_fma_f32 v117, -v50, v29, v27
	v_mul_f32_e32 v23, v82, v82
	v_fmac_f32_e32 v23, v114, v114
	v_fmac_f32_e32 v23, v83, v83
	v_fmac_f32_e32 v23, v115, v115
	v_fmac_f32_e32 v23, v84, v84
	v_fmac_f32_e32 v23, v116, v116
	v_fmac_f32_e32 v23, v85, v85
	v_fmac_f32_e32 v23, v117, v117
	v_lshlrev_b32_e32 v26, 16, v86
	v_and_b32_e32 v27, s4, v86
	v_lshlrev_b32_e32 v28, 16, v118
	v_and_b32_e32 v29, s4, v118
	v_fma_f32 v86, -v50, v28, v26
	v_fma_f32 v118, -v50, v29, v27
	v_lshlrev_b32_e32 v26, 16, v87
	v_and_b32_e32 v27, s4, v87
	v_lshlrev_b32_e32 v28, 16, v119
	v_and_b32_e32 v29, s4, v119
	v_fma_f32 v87, -v50, v28, v26
	v_fma_f32 v119, -v50, v29, v27
	v_lshlrev_b32_e32 v26, 16, v88
	v_and_b32_e32 v27, s4, v88
	v_lshlrev_b32_e32 v28, 16, v120
	v_and_b32_e32 v29, s4, v120
	v_fma_f32 v88, -v50, v28, v26
	v_fma_f32 v120, -v50, v29, v27
	v_lshlrev_b32_e32 v26, 16, v89
	v_and_b32_e32 v27, s4, v89
	v_lshlrev_b32_e32 v28, 16, v121
	v_and_b32_e32 v29, s4, v121
	v_fma_f32 v89, -v50, v28, v26
	v_fma_f32 v121, -v50, v29, v27
	v_mul_f32_e32 v24, v86, v86
	v_fmac_f32_e32 v24, v118, v118
	v_fmac_f32_e32 v24, v87, v87
	v_fmac_f32_e32 v24, v119, v119
	v_fmac_f32_e32 v24, v88, v88
	v_fmac_f32_e32 v24, v120, v120
	v_fmac_f32_e32 v24, v89, v89
	v_fmac_f32_e32 v24, v121, v121
	v_lshlrev_b32_e32 v26, 16, v90
	v_and_b32_e32 v27, s4, v90
	v_lshlrev_b32_e32 v28, 16, v122
	v_and_b32_e32 v29, s4, v122
	v_fma_f32 v90, -v50, v28, v26
	v_fma_f32 v122, -v50, v29, v27
	v_lshlrev_b32_e32 v26, 16, v91
	v_and_b32_e32 v27, s4, v91
	v_lshlrev_b32_e32 v28, 16, v123
	v_and_b32_e32 v29, s4, v123
	v_fma_f32 v91, -v50, v28, v26
	v_fma_f32 v123, -v50, v29, v27
	v_lshlrev_b32_e32 v26, 16, v92
	v_and_b32_e32 v27, s4, v92
	v_lshlrev_b32_e32 v28, 16, v124
	v_and_b32_e32 v29, s4, v124
	v_fma_f32 v92, -v50, v28, v26
	v_fma_f32 v124, -v50, v29, v27
	v_lshlrev_b32_e32 v26, 16, v93
	v_and_b32_e32 v27, s4, v93
	v_lshlrev_b32_e32 v28, 16, v125
	v_and_b32_e32 v29, s4, v125
	v_fma_f32 v93, -v50, v28, v26
	v_fma_f32 v125, -v50, v29, v27
	v_mul_f32_e32 v25, v90, v90
	v_fmac_f32_e32 v25, v122, v122
	v_fmac_f32_e32 v25, v91, v91
	v_fmac_f32_e32 v25, v123, v123
	v_fmac_f32_e32 v25, v92, v92
	v_fmac_f32_e32 v25, v124, v124
	v_fmac_f32_e32 v25, v93, v93
	v_fmac_f32_e32 v25, v125, v125
	ds_swizzle_b32 v26, v18 offset:0x41f
	ds_swizzle_b32 v27, v19 offset:0x41f
	ds_swizzle_b32 v28, v20 offset:0x41f
	ds_swizzle_b32 v29, v21 offset:0x41f
	ds_swizzle_b32 v30, v22 offset:0x41f
	ds_swizzle_b32 v31, v23 offset:0x41f
	ds_swizzle_b32 v32, v24 offset:0x41f
	ds_swizzle_b32 v33, v25 offset:0x41f
	s_waitcnt lgkmcnt(0)
	v_add_f32_e32 v18, v18, v26
	v_add_f32_e32 v19, v19, v27
	v_add_f32_e32 v20, v20, v28
	v_add_f32_e32 v21, v21, v29
	v_add_f32_e32 v22, v22, v30
	v_add_f32_e32 v23, v23, v31
	v_add_f32_e32 v24, v24, v32
	v_add_f32_e32 v25, v25, v33
	ds_swizzle_b32 v26, v18 offset:0x81f
	ds_swizzle_b32 v27, v19 offset:0x81f
	ds_swizzle_b32 v28, v20 offset:0x81f
	ds_swizzle_b32 v29, v21 offset:0x81f
	ds_swizzle_b32 v30, v22 offset:0x81f
	ds_swizzle_b32 v31, v23 offset:0x81f
	ds_swizzle_b32 v32, v24 offset:0x81f
	ds_swizzle_b32 v33, v25 offset:0x81f
	s_waitcnt lgkmcnt(0)
	v_add_f32_e32 v18, v18, v26
	v_add_f32_e32 v19, v19, v27
	v_add_f32_e32 v20, v20, v28
	v_add_f32_e32 v21, v21, v29
	v_add_f32_e32 v22, v22, v30
	v_add_f32_e32 v23, v23, v31
	v_add_f32_e32 v24, v24, v32
	v_add_f32_e32 v25, v25, v33
	ds_swizzle_b32 v26, v18 offset:0x101f
	ds_swizzle_b32 v27, v19 offset:0x101f
	ds_swizzle_b32 v28, v20 offset:0x101f
	ds_swizzle_b32 v29, v21 offset:0x101f
	ds_swizzle_b32 v30, v22 offset:0x101f
	ds_swizzle_b32 v31, v23 offset:0x101f
	ds_swizzle_b32 v32, v24 offset:0x101f
	ds_swizzle_b32 v33, v25 offset:0x101f
	s_waitcnt lgkmcnt(0)
; #define GAS __attribute__((address_space(1)))
; __device__ __forceinline__ unsigned pk2(float lo, float hi) { return f2bf(lo) | (f2bf(hi) << 16); }
; __global__ void __launch_bounds__(NWAVES * 64, 2) mk_fwd(Args args) {
;     ...
;                     ss += __shfl_xor(ss, 1); ss += __shfl_xor(ss, 2); ss += __shfl_xor(ss, 4); ss += __shfl_xor(ss, 8);
;                     const float rn = __builtin_amdgcn_rsqf(ss * (1.0f / 128.0f) + 1e-6f);
;                     v4u w;
; #pragma unroll
;                     for (int i = 0; i < 4; ++i) w[i] = pk2(o[2 * i] * rn * gsc[2 * i], o[2 * i + 1] * rn * gsc[2 * i + 1]);
;                     if (m < M) *(GAS v4u*)(OB + (size_t)m * 512 + 8 * lane) = w; }
	v_add_f32_e32 v18, v18, v26
	v_add_f32_e32 v19, v19, v27
	v_add_f32_e32 v20, v20, v28
	v_add_f32_e32 v21, v21, v29
	v_add_f32_e32 v22, v22, v30
	v_add_f32_e32 v23, v23, v31
	v_add_f32_e32 v24, v24, v32
	v_add_f32_e32 v25, v25, v33
	ds_swizzle_b32 v26, v18 offset:0x201f
	ds_swizzle_b32 v27, v19 offset:0x201f
	ds_swizzle_b32 v28, v20 offset:0x201f
	ds_swizzle_b32 v29, v21 offset:0x201f
	ds_swizzle_b32 v30, v22 offset:0x201f
	ds_swizzle_b32 v31, v23 offset:0x201f
	ds_swizzle_b32 v32, v24 offset:0x201f
	ds_swizzle_b32 v33, v25 offset:0x201f
	s_waitcnt lgkmcnt(0)
	v_add_f32_e32 v18, v18, v26
	v_add_f32_e32 v19, v19, v27
	v_add_f32_e32 v20, v20, v28
	v_add_f32_e32 v21, v21, v29
	v_add_f32_e32 v22, v22, v30
	v_add_f32_e32 v23, v23, v31
	v_add_f32_e32 v24, v24, v32
	v_add_f32_e32 v25, v25, v33
	v_mov_b32_e32 v34, 0x358637bd
	v_fmamk_f32 v18, v18, 0x3c000000, v34
	v_fmamk_f32 v19, v19, 0x3c000000, v34
	v_fmamk_f32 v20, v20, 0x3c000000, v34
	v_fmamk_f32 v21, v21, 0x3c000000, v34
	v_fmamk_f32 v22, v22, 0x3c000000, v34
	v_fmamk_f32 v23, v23, 0x3c000000, v34
	v_fmamk_f32 v24, v24, 0x3c000000, v34
	v_fmamk_f32 v25, v25, 0x3c000000, v34
	v_rsq_f32_e32 v18, v18
	v_rsq_f32_e32 v19, v19
	v_rsq_f32_e32 v20, v20
	v_rsq_f32_e32 v21, v21
	v_rsq_f32_e32 v22, v22
	v_rsq_f32_e32 v23, v23
	v_rsq_f32_e32 v24, v24
	v_rsq_f32_e32 v25, v25
	s_nop 0
	v_mul_f32_e32 v62, v62, v18
	v_mul_f32_e32 v62, v62, v54
	v_mul_f32_e32 v94, v94, v18
	v_mul_f32_e32 v94, v94, v55
	v_mul_f32_e32 v63, v63, v18
	v_mul_f32_e32 v63, v63, v56
	v_mul_f32_e32 v95, v95, v18
	v_mul_f32_e32 v95, v95, v57
	v_mul_f32_e32 v64, v64, v18
	v_mul_f32_e32 v64, v64, v58
	v_mul_f32_e32 v96, v96, v18
	v_mul_f32_e32 v96, v96, v59
	v_mul_f32_e32 v65, v65, v18
	v_mul_f32_e32 v65, v65, v60
	v_mul_f32_e32 v97, v97, v18
	v_mul_f32_e32 v97, v97, v61
	v_cvt_pk_bf16_f32 v26, v62, v94
	v_cvt_pk_bf16_f32 v27, v63, v95
	v_cvt_pk_bf16_f32 v28, v64, v96
	v_cvt_pk_bf16_f32 v29, v65, v97
	global_store_dwordx4 v53, v[26:29], s[42:43]
	s_nop 1
	v_mul_f32_e32 v66, v66, v19
	v_mul_f32_e32 v66, v66, v54
	v_mul_f32_e32 v98, v98, v19
	v_mul_f32_e32 v98, v98, v55
	v_mul_f32_e32 v67, v67, v19
	v_mul_f32_e32 v67, v67, v56
	v_mul_f32_e32 v99, v99, v19
	v_mul_f32_e32 v99, v99, v57
	v_mul_f32_e32 v68, v68, v19
	v_mul_f32_e32 v68, v68, v58
	v_mul_f32_e32 v100, v100, v19
	v_mul_f32_e32 v100, v100, v59
	v_mul_f32_e32 v69, v69, v19
	v_mul_f32_e32 v69, v69, v60
	v_mul_f32_e32 v101, v101, v19
	v_mul_f32_e32 v101, v101, v61
	v_cvt_pk_bf16_f32 v26, v66, v98
	v_cvt_pk_bf16_f32 v27, v67, v99
	v_cvt_pk_bf16_f32 v28, v68, v100
	v_cvt_pk_bf16_f32 v29, v69, v101
	v_add_u32_e32 v126, 0x1000, v53
	global_store_dwordx4 v126, v[26:29], s[42:43]
	s_nop 1
	v_mul_f32_e32 v70, v70, v20
	v_mul_f32_e32 v70, v70, v54
	v_mul_f32_e32 v102, v102, v20
	v_mul_f32_e32 v102, v102, v55
	v_mul_f32_e32 v71, v71, v20
	v_mul_f32_e32 v71, v71, v56
	v_mul_f32_e32 v103, v103, v20
	v_mul_f32_e32 v103, v103, v57
	v_mul_f32_e32 v72, v72, v20
	v_mul_f32_e32 v72, v72, v58
	v_mul_f32_e32 v104, v104, v20
	v_mul_f32_e32 v104, v104, v59
	v_mul_f32_e32 v73, v73, v20
	v_mul_f32_e32 v73, v73, v60
	v_mul_f32_e32 v105, v105, v20
	v_mul_f32_e32 v105, v105, v61
	v_cvt_pk_bf16_f32 v26, v70, v102
	v_cvt_pk_bf16_f32 v27, v71, v103
	v_cvt_pk_bf16_f32 v28, v72, v104
	v_cvt_pk_bf16_f32 v29, v73, v105
	v_add_u32_e32 v126, 0x2000, v53
	global_store_dwordx4 v126, v[26:29], s[42:43]
	s_nop 1
	v_mul_f32_e32 v74, v74, v21
	v_mul_f32_e32 v74, v74, v54
	v_mul_f32_e32 v106, v106, v21
	v_mul_f32_e32 v106, v106, v55
	v_mul_f32_e32 v75, v75, v21
	v_mul_f32_e32 v75, v75, v56
	v_mul_f32_e32 v107, v107, v21
	v_mul_f32_e32 v107, v107, v57
	v_mul_f32_e32 v76, v76, v21
	v_mul_f32_e32 v76, v76, v58
	v_mul_f32_e32 v108, v108, v21
	v_mul_f32_e32 v108, v108, v59
	v_mul_f32_e32 v77, v77, v21
	v_mul_f32_e32 v77, v77, v60
	v_mul_f32_e32 v109, v109, v21
	v_mul_f32_e32 v109, v109, v61
	v_cvt_pk_bf16_f32 v26, v74, v106
	v_cvt_pk_bf16_f32 v27, v75, v107
	v_cvt_pk_bf16_f32 v28, v76, v108
	v_cvt_pk_bf16_f32 v29, v77, v109
	v_add_u32_e32 v126, 0x3000, v53
	global_store_dwordx4 v126, v[26:29], s[42:43]
	s_nop 1
	v_mul_f32_e32 v78, v78, v22
	v_mul_f32_e32 v78, v78, v54
	v_mul_f32_e32 v110, v110, v22
	v_mul_f32_e32 v110, v110, v55
	v_mul_f32_e32 v79, v79, v22
	v_mul_f32_e32 v79, v79, v56
	v_mul_f32_e32 v111, v111, v22
	v_mul_f32_e32 v111, v111, v57
	v_mul_f32_e32 v80, v80, v22
	v_mul_f32_e32 v80, v80, v58
	v_mul_f32_e32 v112, v112, v22
	v_mul_f32_e32 v112, v112, v59
	v_mul_f32_e32 v81, v81, v22
	v_mul_f32_e32 v81, v81, v60
	v_mul_f32_e32 v113, v113, v22
	v_mul_f32_e32 v113, v113, v61
	v_cvt_pk_bf16_f32 v26, v78, v110
	v_cvt_pk_bf16_f32 v27, v79, v111
	v_cvt_pk_bf16_f32 v28, v80, v112
	v_cvt_pk_bf16_f32 v29, v81, v113
	v_add_u32_e32 v126, 0x4000, v53
	global_store_dwordx4 v126, v[26:29], s[42:43]
	s_nop 1
	v_mul_f32_e32 v82, v82, v23
	v_mul_f32_e32 v82, v82, v54
	v_mul_f32_e32 v114, v114, v23
	v_mul_f32_e32 v114, v114, v55
	v_mul_f32_e32 v83, v83, v23
	v_mul_f32_e32 v83, v83, v56
	v_mul_f32_e32 v115, v115, v23
	v_mul_f32_e32 v115, v115, v57
	v_mul_f32_e32 v84, v84, v23
	v_mul_f32_e32 v84, v84, v58
	v_mul_f32_e32 v116, v116, v23
	v_mul_f32_e32 v116, v116, v59
	v_mul_f32_e32 v85, v85, v23
	v_mul_f32_e32 v85, v85, v60
	v_mul_f32_e32 v117, v117, v23
	v_mul_f32_e32 v117, v117, v61
	v_cvt_pk_bf16_f32 v26, v82, v114
	v_cvt_pk_bf16_f32 v27, v83, v115
	v_cvt_pk_bf16_f32 v28, v84, v116
	v_cvt_pk_bf16_f32 v29, v85, v117
	v_add_u32_e32 v126, 0x5000, v53
	global_store_dwordx4 v126, v[26:29], s[42:43]
	s_nop 1
	v_mul_f32_e32 v86, v86, v24
	v_mul_f32_e32 v86, v86, v54
	v_mul_f32_e32 v118, v118, v24
	v_mul_f32_e32 v118, v118, v55
	v_mul_f32_e32 v87, v87, v24
	v_mul_f32_e32 v87, v87, v56
	v_mul_f32_e32 v119, v119, v24
	v_mul_f32_e32 v119, v119, v57
	v_mul_f32_e32 v88, v88, v24
	v_mul_f32_e32 v88, v88, v58
	v_mul_f32_e32 v120, v120, v24
	v_mul_f32_e32 v120, v120, v59
	v_mul_f32_e32 v89, v89, v24
	v_mul_f32_e32 v89, v89, v60
	v_mul_f32_e32 v121, v121, v24
	v_mul_f32_e32 v121, v121, v61
	v_cvt_pk_bf16_f32 v26, v86, v118
	v_cvt_pk_bf16_f32 v27, v87, v119
	v_cvt_pk_bf16_f32 v28, v88, v120
	v_cvt_pk_bf16_f32 v29, v89, v121
	v_add_u32_e32 v126, 0x6000, v53
	global_store_dwordx4 v126, v[26:29], s[42:43]
	s_nop 1
	v_mul_f32_e32 v90, v90, v25
	v_mul_f32_e32 v90, v90, v54
	v_mul_f32_e32 v122, v122, v25
	v_mul_f32_e32 v122, v122, v55
	v_mul_f32_e32 v91, v91, v25
	v_mul_f32_e32 v91, v91, v56
	v_mul_f32_e32 v123, v123, v25
	v_mul_f32_e32 v123, v123, v57
	v_mul_f32_e32 v92, v92, v25
	v_mul_f32_e32 v92, v92, v58
	v_mul_f32_e32 v124, v124, v25
	v_mul_f32_e32 v124, v124, v59
	v_mul_f32_e32 v93, v93, v25
	v_mul_f32_e32 v93, v93, v60
	v_mul_f32_e32 v125, v125, v25
	v_mul_f32_e32 v125, v125, v61
	v_cvt_pk_bf16_f32 v26, v90, v122
	v_cvt_pk_bf16_f32 v27, v91, v123
	v_cvt_pk_bf16_f32 v28, v92, v124
	v_cvt_pk_bf16_f32 v29, v93, v125
	v_add_u32_e32 v126, 0x7000, v53
	global_store_dwordx4 v126, v[26:29], s[42:43]
	s_nop 1

; __global__ void __launch_bounds__(NWAVES * 64, 2) mk_fwd(Args args) {
;     ...
;                         const int s = v & 7, bhv = (v >> 3) + 32 * (i >> 2), ii = i & 3, b = bhv >> 4, h = (bhv >> 2) & 3, c = (bhv >> 1) & 1, vh = bhv & 1;
;                         qb = (ii == 0) ? s : (ii == 1) ? 15 - s : (ii == 2) ? 16 + s : 31 - s; t0 = 0; win = false; rowbase = (long)b * SEQ;
;                         qc = 768 + h * 128 + c * 64; kc = 1280 + h * 128 + c * 64; vc = 1792 + h * 128 + vh * 64; oc = h * 128 + vh * 64; Ob = c ? OD1 : OD0;
.LBB0_257:
	s_lshl_b32 s4, s75, 2
	s_and_b32 s4, s4, 32
	s_add_i32 s4, s4, s77
	s_ashr_i32 s42, s4, 4
	s_lshr_b32 s42, s75, 6
	s_and_b32 s2, s75, 15
	s_xor_b32 s4, s2, 31
	s_cmp_lt_u32 s85, 2
	s_cselect_b32 s2, s2, s4
	s_and_b32 s4, s85, 1
	s_lshl_b32 s88, s4, 6
	s_add_i32 s88, s88, s33
	s_add_i32 s89, s88, 0x500
	s_addk_i32 s88, 0x300
	s_cmp_eq_u32 s4, 0
	s_mov_b32 s56, 0x17000000
	s_cselect_b32 s56, s56, 0x19000000
	s_mov_b64 s[44:45], 0

;   #define PIN(x) asm volatile("":"+v"(x))
; __device__ __forceinline__ void unit_qk_offsets(int vv,int ii,long&qo,long&ko){
;   int q_,t_,qc_,kc_; long rb;
;   if(ii<8){ const int s=vv&7,bhv=(vv>>3)+32*(ii>>2),i4=ii&3,b=bhv>>4,h=(bhv>>2)&3,c=(bhv>>1)&1;
;     q_=(i4==0)?s:(i4==1)?15-s:(i4==2)?16+s:31-s; t_=0; rb=(long)b*SEQ; qc_=768+h*128+c*64; kc_=1280+h*128+c*64; }
;   else{ const int ui=vv*4+(ii-8),hq=(ui>>5)&7,b=ui>>8; q_=ui&31; t_=q_>0?4*q_-2:0; rb=(long)b*SEQ; qc_=hq*64; kc_=512+(hq>>2)*64; }
;   qo=qc_+(rb+(long)q_*QB)*PIN; ko=kc_+(rb+(long)t_*KVBLK)*PIN;
.LBB0_619:
	s_and_b32 s42, s43, 15
	s_xor_b32 s4, s42, 31
	s_cmp_lt_u32 s48, 2
	s_cselect_b32 s42, s42, s4
	s_lshr_b32 s44, s43, 6
	s_lshl_b32 s4, s43, 3
	s_and_b32 s4, s4, 0x180
	s_and_b32 s43, s48, 1
	s_lshl_b32 s43, s43, 6
	s_or_b32 s43, s43, s4
	s_add_i32 s4, s43, 0x300
	s_add_i32 s64, s43, 0x500
	s_mov_b64 s[62:63], 0

; __global__ void __launch_bounds__(NWAVES * 64, 2) mk_fwd(Args args) {
;     ...
;         {
;             LANE_WAVE();
;             kargs_t ap = KARGS(); bf16* OD0 = WSP(bf16, WS_OD0); bf16* OD1 = WSP(bf16, WS_OD1); bf16* OB = WSP(bf16, WS_OB);
;             const float lam_init = 0.8f - 0.6f * expf(-0.3f * (float)l);
;             const float* lp = ap->in[10] + l * 256;
;             const float lam = expf(wave_sum(lp[lane] * lp[64 + lane])) - expf(wave_sum(lp[128 + lane] * lp[192 + lane])) + lam_init;
;             const float* sl = ap->in[11] + l * 128 + (8 * lane & 127);
;             float gsc[8];
; #pragma unroll
;             for (int i = 0; i < 8; ++i) gsc[i] = sl[i] * (1.0f - lam_init);
;             for (int m0 = gw; m0 < M; m0 += 4 * NGW) {
;                 v4u a[4], b[4];
; #pragma unroll
;                 for (int j = 0; j < 4; ++j) { const int m = m0 + j * NGW; if (m < M) { a[j] = *(const GAS v4u*)(OD0 + (size_t)m * 512 + 8 * lane); b[j] = *(const GAS v4u*)(OD1 + (size_t)m * 512 + 8 * lane); } else { a[j] = (v4u){0u, 0u, 0u, 0u}; b[j] = a[j]; } }
; #pragma unroll
;                 for (int j = 0; j < 4; ++j) { const int m = m0 + j * NGW;
;                     float o[8];
; #pragma unroll
;                     for (int i = 0; i < 4; ++i) { o[2 * i] = __uint_as_float(a[j][i] << 16) - lam * __uint_as_float(b[j][i] << 16); o[2 * i + 1] = __uint_as_float(a[j][i] & 0xffff0000u) - lam * __uint_as_float(b[j][i] & 0xffff0000u); }
;                     float ss = 0.f;
; #pragma unroll
;                     for (int i = 0; i < 8; ++i) ss += o[i] * o[i];
;                     ss += __shfl_xor(ss, 1); ss += __shfl_xor(ss, 2); ss += __shfl_xor(ss, 4); ss += __shfl_xor(ss, 8);
;                     const float rn = __builtin_amdgcn_rsqf(ss * (1.0f / 128.0f) + 1e-6f);
;                     v4u w;
; #pragma unroll
;                     for (int i = 0; i < 4; ++i) w[i] = pk2(o[2 * i] * rn * gsc[2 * i], o[2 * i + 1] * rn * gsc[2 * i + 1]);
;                     if (m < M) *(GAS v4u*)(OB + (size_t)m * 512 + 8 * lane) = w; }
;             }
;         }
;         GRID_SYNC();
;         {
;             kargs_t ap = KARGS();
;             pg8::Gemm g{WSP(bf16, WS_OA), WB(l, WS_WB), M, DM, 512, (size_t)(WS_OB - WS_OA), (size_t)DM * 512 * 2}; pg8::ZOrder S; S.S.init(M, DM, G, bx);
;             pg8::EpiGateMerge E{WSP(bf16, WS_GATE), WSP(bf16, WS_MRG)};
.LBB0_679:
	s_or_b64 exec, exec, s[38:39]
	v_readlane_b32 s44, v253, 2
	s_waitcnt lgkmcnt(0)
	v_mov_b32_e32 v18, v212
	v_readlane_b32 s45, v253, 3
	s_barrier
	v_readlane_b32 s42, v253, 2
	v_readlane_b32 s43, v253, 3
	s_branch .Lmy_p4
.Lmy_p4:
	s_load_dwordx2 s[38:39], s[42:43], 0x78
	v_readlane_b32 s2, v252, 9
	v_readlane_b32 s3, v252, 10
	s_and_b64 vcc, exec, s[2:3]
	s_waitcnt lgkmcnt(0)
	s_mov_b64 s[40:41], s[38:39]
	s_cbranch_vccz .LBB0_754
	s_load_dwordx2 s[40:41], s[42:43], 0x70
